# speedup vs baseline: 1.0209x; 1.0037x over previous
; __device__ __forceinline__ unsigned cvt_pk_bf16(float lo, float hi) { unsigned r; asm volatile("v_cvt_pk_bf16_f32 %0, %1, %2" : "=v"(r) : "v"(lo), "v"(hi)); return r; }
; #define LAS __attribute__((address_space(3)))
; __device__ __forceinline__ float bflo(unsigned w) { return __uint_as_float(w << 16); }
; __device__ __forceinline__ float bfhi(unsigned w) { return __uint_as_float(w & 0xffff0000u); }
; __device__ __forceinline__ void spatial_phase(LAS unsigned char* lds, const float* w_s, const float* b_s, const float* normg, const float* ssq, const bf16_t* GVT, bf16_t* U) {
;     ...
;             if (tid < 128) rs[tid] = rsqrtf(((red[tid] + red[128 + tid]) + (red[256 + tid] + red[384 + tid])) * (1.0f / GMW) + EPS);
;             __syncthreads();
; #pragma unroll
;             for (int q = 0; q < 4; ++q) { const f32x4 sa = *(const LAS f32x4*)(rs + 32 * cgp + 8 * q), sb = *(const LAS f32x4*)(rs + 32 * cgp + 8 * q + 4);
;                 const f32x4 pa = wa[q] * sa, pb = wb[q] * sb; u32x4 o; o.x = cvt_pk_bf16(pa[0], pa[1]); o.y = cvt_pk_bf16(pa[2], pa[3]); o.z = cvt_pk_bf16(pb[0], pb[1]); o.w = cvt_pk_bf16(pb[2], pb[3]);
;                 *(LAS u32x4*)(lds + (cgp * 4 + q) * 2048 + i_st * 16) = o; } }
;         __syncthreads();
; #pragma unroll
;         for (int ib = 0; ib < 4; ++ib) {
;             f32x16 acc = {};
; #pragma unroll
;             for (int kk = 0; kk < 8; ++kk) { const bf16x8 af = *(const LAS bf16x8*)(lds + (2 * kk + hi) * 2048 + (32 * ib + r32) * 16);
;                 acc = __builtin_amdgcn_mfma_f32_32x32x16_bf16(bfr[kk], af, acc, 0, 0, 0); }
;             const int i = 32 * ib + r32; bf16_t* up = U + (size_t)(c * 128 + i) * GMW + g * 256 + 32 * wid + 4 * hi;
; #pragma unroll
;             for (int q4 = 0; q4 < 4; ++q4) { const u32x2 u2 = uu[ib][q4]; const float bb = bsv[ib];
;                 const float o0 = bflo(u2.x) * (acc[4 * q4 + 0] * ng[q4][0] + bb), o1 = bfhi(u2.x) * (acc[4 * q4 + 1] * ng[q4][1] + bb), o2 = bflo(u2.y) * (acc[4 * q4 + 2] * ng[q4][2] + bb), o3 = bfhi(u2.y) * (acc[4 * q4 + 3] * ng[q4][3] + bb);
;                 u32x2 w; w.x = cvt_pk_bf16(o0, o1); w.y = cvt_pk_bf16(o2, o3); *(u32x2*)(up + 8 * q4) = w; }
.LBB0_205:
	s_or_b64 exec, exec, s[10:11]
	s_waitcnt lgkmcnt(0)
	s_barrier
	ds_read_b128 v[152:155], v142 offset:34816
	ds_read_b128 v[156:159], v142 offset:34832
	s_add_i32 s13, s13, s50
	s_cmpk_lt_i32 s13, 0x1080
	s_waitcnt vmcnt(28) lgkmcnt(1)
	v_pk_mul_f32 v[76:77], v[76:77], v[152:153]
	s_waitcnt lgkmcnt(0)
	v_pk_mul_f32 v[152:153], v[74:75], v[158:159]
	v_pk_mul_f32 v[74:75], v[72:73], v[156:157]
	v_pk_mul_f32 v[78:79], v[78:79], v[154:155]
	v_cvt_pk_bf16_f32 v72, v76, v77
	s_nop 0
	v_cvt_pk_bf16_f32 v73, v78, v79
	v_cvt_pk_bf16_f32 v74, v74, v75
	v_cvt_pk_bf16_f32 v75, v152, v153
	ds_write_b128 v148, v[72:75]
	ds_read_b128 v[72:75], v142 offset:34848
	ds_read_b128 v[76:79], v142 offset:34864
	s_waitcnt lgkmcnt(1)
	v_pk_mul_f32 v[68:69], v[68:69], v[72:73]
	s_waitcnt lgkmcnt(0)
	v_pk_mul_f32 v[72:73], v[66:67], v[78:79]
	v_pk_mul_f32 v[66:67], v[64:65], v[76:77]
	v_pk_mul_f32 v[70:71], v[70:71], v[74:75]
	v_cvt_pk_bf16_f32 v64, v68, v69
	s_waitcnt vmcnt(15)
	s_waitcnt vmcnt(15)
	v_permlane32_swap_b32 v136, v138
	v_permlane32_swap_b32 v137, v139
	v_lshlrev_b32_e32 v74, 16, v139
	v_cvt_pk_bf16_f32 v65, v70, v71
	v_cvt_pk_bf16_f32 v66, v66, v67
	v_cvt_pk_bf16_f32 v67, v72, v73
	ds_write_b128 v148, v[64:67] offset:2048
	ds_read_b128 v[64:67], v142 offset:34880
	ds_read_b128 v[68:71], v142 offset:34896
	v_lshlrev_b32_e32 v72, 16, v138
	v_and_b32_e32 v73, 0xffff0000, v138
	v_and_b32_e32 v75, 0xffff0000, v139
	s_waitcnt lgkmcnt(1)
	v_pk_mul_f32 v[12:13], v[12:13], v[64:65]
	s_waitcnt lgkmcnt(0)
	v_pk_mul_f32 v[64:65], v[10:11], v[70:71]
	v_pk_mul_f32 v[10:11], v[8:9], v[68:69]
	v_pk_mul_f32 v[14:15], v[14:15], v[66:67]
	v_cvt_pk_bf16_f32 v8, v12, v13
	s_waitcnt vmcnt(14)
	s_waitcnt vmcnt(14)
	v_permlane32_swap_b32 v132, v134
	v_permlane32_swap_b32 v133, v135
	v_lshlrev_b32_e32 v76, 16, v134
	v_cvt_pk_bf16_f32 v9, v14, v15
	v_cvt_pk_bf16_f32 v10, v10, v11
	v_cvt_pk_bf16_f32 v11, v64, v65
	ds_write_b128 v148, v[8:11] offset:4096
	ds_read_b128 v[8:11], v142 offset:34912
	ds_read_b128 v[12:15], v142 offset:34928
	v_and_b32_e32 v77, 0xffff0000, v134
	v_lshlrev_b32_e32 v78, 16, v135
	s_waitcnt vmcnt(13)
	s_waitcnt vmcnt(13)
	v_permlane32_swap_b32 v128, v130
	v_permlane32_swap_b32 v129, v131
	v_and_b32_e32 v79, 0xffff0000, v131
	s_waitcnt lgkmcnt(1)
	v_pk_mul_f32 v[4:5], v[4:5], v[8:9]
	s_waitcnt lgkmcnt(0)
	v_pk_mul_f32 v[8:9], v[2:3], v[14:15]
	v_pk_mul_f32 v[2:3], v[0:1], v[12:13]
	v_pk_mul_f32 v[6:7], v[6:7], v[10:11]
	v_cvt_pk_bf16_f32 v0, v4, v5
	s_nop 0
	v_cvt_pk_bf16_f32 v1, v6, v7
	v_cvt_pk_bf16_f32 v2, v2, v3
	v_cvt_pk_bf16_f32 v3, v8, v9
	ds_write_b128 v148, v[0:3] offset:6144
	s_waitcnt lgkmcnt(0)
	s_barrier
	ds_read_b128 v[0:3], v149
	ds_read_b128 v[64:67], v149 offset:4096
	s_waitcnt lgkmcnt(1)
	v_mfma_f32_32x32x16_bf16 v[0:15], v[56:59], v[0:3], 0
	s_waitcnt lgkmcnt(0)
	v_mfma_f32_32x32x16_bf16 v[0:15], v[52:55], v[64:67], v[0:15]
	ds_read_b128 v[64:67], v149 offset:8192
	ds_read_b128 v[68:71], v149 offset:12288
	s_waitcnt lgkmcnt(1)
	v_mfma_f32_32x32x16_bf16 v[0:15], v[48:51], v[64:67], v[0:15]
	s_waitcnt lgkmcnt(0)
	v_mfma_f32_32x32x16_bf16 v[0:15], v[44:47], v[68:71], v[0:15]
	ds_read_b128 v[64:67], v149 offset:16384
	ds_read_b128 v[68:71], v149 offset:20480
	s_waitcnt lgkmcnt(1)
	v_mfma_f32_32x32x16_bf16 v[0:15], v[40:43], v[64:67], v[0:15]
	ds_read_b128 v[64:67], v149 offset:24576
	s_waitcnt lgkmcnt(1)
	v_mfma_f32_32x32x16_bf16 v[0:15], v[36:39], v[68:71], v[0:15]
	ds_read_b128 v[68:71], v149 offset:28672
	s_waitcnt lgkmcnt(1)
	v_mfma_f32_32x32x16_bf16 v[0:15], v[24:27], v[64:67], v[0:15]
	v_lshlrev_b32_e32 v64, 16, v136
	v_and_b32_e32 v65, 0xffff0000, v136
	v_lshlrev_b32_e32 v66, 16, v137
	v_and_b32_e32 v67, 0xffff0000, v137
	s_waitcnt lgkmcnt(0)
	v_mfma_f32_32x32x16_bf16 v[0:15], v[16:19], v[68:71], v[0:15]
	s_waitcnt vmcnt(5)
	s_nop 10
	v_fma_f32 v0, v60, v0, v151
	v_fma_f32 v1, v61, v1, v151
	v_fma_f32 v2, v62, v2, v151
	v_fma_f32 v3, v63, v3, v151
	v_mul_f32_e32 v0, v0, v72
	v_mul_f32_e32 v1, v1, v73
	s_waitcnt vmcnt(4)
	v_fma_f32 v4, v32, v4, v151
	v_fma_f32 v5, v33, v5, v151
	v_fma_f32 v6, v34, v6, v151
	v_fma_f32 v7, v35, v7, v151
	v_mul_f32_e32 v2, v2, v74
	v_mul_f32_e32 v3, v3, v75
	v_cvt_pk_bf16_f32 v214, v0, v1
	v_cvt_pk_bf16_f32 v215, v2, v3
	v_mul_f32_e32 v4, v4, v64
	v_mul_f32_e32 v5, v5, v65
	v_mul_f32_e32 v6, v6, v66
	v_mul_f32_e32 v7, v7, v67
	v_cvt_pk_bf16_f32 v212, v4, v5
	v_cvt_pk_bf16_f32 v213, v6, v7
	s_nop 1
	v_permlane32_swap_b32 v212, v214
	v_permlane32_swap_b32 v213, v215
	v_lshl_add_u64 v[162:163], v[126:127], 0, v[160:161]
	global_store_dwordx4 v[162:163], v[212:215], off
	v_and_b32_e32 v0, 0xffff0000, v135
	s_waitcnt vmcnt(4)
	v_fma_f32 v1, v31, v11, v151
	v_fma_f32 v8, v28, v8, v151
	v_fma_f32 v9, v29, v9, v151
	v_fma_f32 v10, v30, v10, v151
	v_mul_f32_e32 v1, v1, v0
	v_mul_f32_e32 v8, v8, v76
	v_mul_f32_e32 v9, v9, v77
	v_mul_f32_e32 v10, v10, v78
	v_cvt_pk_bf16_f32 v218, v8, v9
	v_cvt_pk_bf16_f32 v219, v10, v1
	v_lshlrev_b32_e32 v0, 16, v132
	s_waitcnt vmcnt(3)
	v_fma_f32 v1, v20, v12, v151
	v_mul_f32_e32 v0, v1, v0
	v_and_b32_e32 v1, 0xffff0000, v132
	v_fma_f32 v2, v21, v13, v151
	v_mul_f32_e32 v1, v2, v1
	v_lshlrev_b32_e32 v2, 16, v133
	v_fma_f32 v3, v22, v14, v151
	v_mul_f32_e32 v2, v3, v2
	v_and_b32_e32 v3, 0xffff0000, v133
	v_fmac_f32_e32 v151, v23, v15
	v_mul_f32_e32 v3, v151, v3
	v_cvt_pk_bf16_f32 v216, v0, v1
	v_cvt_pk_bf16_f32 v217, v2, v3
	ds_read_b128 v[0:3], v149 offset:512
	ds_read_b128 v[64:67], v149 offset:4608
	s_waitcnt lgkmcnt(1)
; __device__ __forceinline__ unsigned cvt_pk_bf16(float lo, float hi) { unsigned r; asm volatile("v_cvt_pk_bf16_f32 %0, %1, %2" : "=v"(r) : "v"(lo), "v"(hi)); return r; }
; #define LAS __attribute__((address_space(3)))
; __device__ __forceinline__ float bflo(unsigned w) { return __uint_as_float(w << 16); }
; __device__ __forceinline__ float bfhi(unsigned w) { return __uint_as_float(w & 0xffff0000u); }
; __device__ __forceinline__ void spatial_phase(LAS unsigned char* lds, const float* w_s, const float* b_s, const float* normg, const float* ssq, const bf16_t* GVT, bf16_t* U) {
;     ...
;         for (int ib = 0; ib < 4; ++ib) {
;             f32x16 acc = {};
; #pragma unroll
;             for (int kk = 0; kk < 8; ++kk) { const bf16x8 af = *(const LAS bf16x8*)(lds + (2 * kk + hi) * 2048 + (32 * ib + r32) * 16);
;                 acc = __builtin_amdgcn_mfma_f32_32x32x16_bf16(bfr[kk], af, acc, 0, 0, 0); }
;             const int i = 32 * ib + r32; bf16_t* up = U + (size_t)(c * 128 + i) * GMW + g * 256 + 32 * wid + 4 * hi;
; #pragma unroll
;             for (int q4 = 0; q4 < 4; ++q4) { const u32x2 u2 = uu[ib][q4]; const float bb = bsv[ib];
;                 const float o0 = bflo(u2.x) * (acc[4 * q4 + 0] * ng[q4][0] + bb), o1 = bfhi(u2.x) * (acc[4 * q4 + 1] * ng[q4][1] + bb), o2 = bflo(u2.y) * (acc[4 * q4 + 2] * ng[q4][2] + bb), o3 = bfhi(u2.y) * (acc[4 * q4 + 3] * ng[q4][3] + bb);
;                 u32x2 w; w.x = cvt_pk_bf16(o0, o1); w.y = cvt_pk_bf16(o2, o3); *(u32x2*)(up + 8 * q4) = w; }
	v_mfma_f32_32x32x16_bf16 v[0:15], v[56:59], v[0:3], 0
	v_or_b32_e32 v74, 32, v108
	v_lshlrev_b32_e32 v76, 16, v130
	v_and_b32_e32 v77, 0xffff0000, v130
	v_ashrrev_i32_e32 v75, 31, v74
	v_lshlrev_b32_e32 v78, 16, v131
	v_lshlrev_b32_e32 v130, 16, v128
	v_and_b32_e32 v128, 0xffff0000, v128
	s_waitcnt lgkmcnt(0)
	v_mfma_f32_32x32x16_bf16 v[0:15], v[52:55], v[64:67], v[0:15]
	ds_read_b128 v[64:67], v149 offset:8704
	ds_read_b128 v[68:71], v149 offset:12800
	s_waitcnt lgkmcnt(1)
	v_mfma_f32_32x32x16_bf16 v[0:15], v[48:51], v[64:67], v[0:15]
	s_waitcnt lgkmcnt(0)
	v_mfma_f32_32x32x16_bf16 v[0:15], v[44:47], v[68:71], v[0:15]
	ds_read_b128 v[64:67], v149 offset:16896
	ds_read_b128 v[68:71], v149 offset:20992
	s_nop 1
	v_permlane32_swap_b32 v216, v218
	v_permlane32_swap_b32 v217, v219
	v_lshl_add_u64 v[162:163], v[126:127], 0, v[160:161]
	global_store_dwordx4 v[162:163], v[216:219], off offset:32
	s_waitcnt lgkmcnt(1)
	v_mfma_f32_32x32x16_bf16 v[0:15], v[40:43], v[64:67], v[0:15]
	ds_read_b128 v[64:67], v149 offset:25088
	s_waitcnt lgkmcnt(1)
	v_mfma_f32_32x32x16_bf16 v[0:15], v[36:39], v[68:71], v[0:15]
	ds_read_b128 v[68:71], v149 offset:29184
	s_waitcnt lgkmcnt(1)
	v_mfma_f32_32x32x16_bf16 v[0:15], v[24:27], v[64:67], v[0:15]
	v_lshlrev_b64 v[64:65], 12, v[74:75]
	v_lshlrev_b32_e32 v66, 16, v129
	v_and_b32_e32 v67, 0xffff0000, v129
	v_lshl_add_u64 v[74:75], v[102:103], 0, v[64:65]
	s_waitcnt vmcnt(14)
	v_permlane32_swap_b32 v122, v124
	v_permlane32_swap_b32 v123, v125
	v_lshlrev_b32_e32 v129, 16, v124
	s_waitcnt lgkmcnt(0)
	v_mfma_f32_32x32x16_bf16 v[0:15], v[16:19], v[68:71], v[0:15]
	s_nop 11
	v_fma_f32 v0, v60, v0, v150
	v_fma_f32 v1, v61, v1, v150
	v_fma_f32 v2, v62, v2, v150
	v_fma_f32 v3, v63, v3, v150
	v_mul_f32_e32 v0, v0, v76
	v_mul_f32_e32 v1, v1, v77
	v_fma_f32 v4, v32, v4, v150
	v_fma_f32 v5, v33, v5, v150
	v_fma_f32 v6, v34, v6, v150
	v_fma_f32 v7, v35, v7, v150
	v_mul_f32_e32 v2, v2, v78
	v_mul_f32_e32 v3, v3, v79
	v_cvt_pk_bf16_f32 v222, v0, v1
	v_cvt_pk_bf16_f32 v223, v2, v3
	v_mul_f32_e32 v4, v4, v130
	v_mul_f32_e32 v5, v5, v128
	v_mul_f32_e32 v6, v6, v66
	v_mul_f32_e32 v7, v7, v67
	v_cvt_pk_bf16_f32 v220, v4, v5
	v_cvt_pk_bf16_f32 v221, v6, v7
	s_nop 1
	v_permlane32_swap_b32 v220, v222
	v_permlane32_swap_b32 v221, v223
	v_lshl_add_u64 v[162:163], v[74:75], 0, v[160:161]
	global_store_dwordx4 v[162:163], v[220:223], off
	v_and_b32_e32 v0, 0xffff0000, v124
	v_fma_f32 v1, v29, v9, v150
	v_mul_f32_e32 v0, v1, v0
	v_lshlrev_b32_e32 v1, 16, v125
	v_fma_f32 v2, v30, v10, v150
	v_fma_f32 v8, v28, v8, v150
	v_mul_f32_e32 v1, v2, v1
	v_and_b32_e32 v2, 0xffff0000, v125
	v_fma_f32 v3, v31, v11, v150
	v_mul_f32_e32 v8, v8, v129
	v_mul_f32_e32 v2, v3, v2
	v_cvt_pk_bf16_f32 v226, v8, v0
	v_cvt_pk_bf16_f32 v227, v1, v2
	v_lshlrev_b32_e32 v0, 16, v122
	v_fma_f32 v1, v20, v12, v150
	v_mul_f32_e32 v0, v1, v0
	v_and_b32_e32 v1, 0xffff0000, v122
	v_fma_f32 v2, v21, v13, v150
	v_mul_f32_e32 v1, v2, v1
	v_lshlrev_b32_e32 v2, 16, v123
	v_fma_f32 v3, v22, v14, v150
	v_mul_f32_e32 v2, v3, v2
	v_and_b32_e32 v3, 0xffff0000, v123
	v_fmac_f32_e32 v150, v23, v15
	v_mul_f32_e32 v3, v150, v3
	v_cvt_pk_bf16_f32 v224, v0, v1
	v_cvt_pk_bf16_f32 v225, v2, v3
	ds_read_b128 v[0:3], v149 offset:1024
	ds_read_b128 v[64:67], v149 offset:5120
	s_waitcnt lgkmcnt(1)
	v_mfma_f32_32x32x16_bf16 v[0:15], v[56:59], v[0:3], 0
	v_or_b32_e32 v76, 64, v108
	s_waitcnt vmcnt(14)
	v_permlane32_swap_b32 v118, v120
	v_permlane32_swap_b32 v119, v121
	v_lshlrev_b32_e32 v78, 16, v120
	v_and_b32_e32 v79, 0xffff0000, v120
	v_ashrrev_i32_e32 v77, 31, v76
	v_lshlrev_b32_e32 v120, 16, v121
	v_and_b32_e32 v121, 0xffff0000, v121
	v_lshlrev_b32_e32 v122, 16, v118
	s_waitcnt lgkmcnt(0)
	v_mfma_f32_32x32x16_bf16 v[0:15], v[52:55], v[64:67], v[0:15]
	ds_read_b128 v[64:67], v149 offset:9216
	ds_read_b128 v[68:71], v149 offset:13312
	s_waitcnt lgkmcnt(1)
	v_mfma_f32_32x32x16_bf16 v[0:15], v[48:51], v[64:67], v[0:15]
	s_waitcnt lgkmcnt(0)
	v_mfma_f32_32x32x16_bf16 v[0:15], v[44:47], v[68:71], v[0:15]
	ds_read_b128 v[64:67], v149 offset:17408
	ds_read_b128 v[68:71], v149 offset:21504
	s_nop 1
	v_permlane32_swap_b32 v224, v226
	v_permlane32_swap_b32 v225, v227
	v_lshl_add_u64 v[162:163], v[74:75], 0, v[160:161]
	global_store_dwordx4 v[162:163], v[224:227], off offset:32
	s_waitcnt lgkmcnt(1)
	v_mfma_f32_32x32x16_bf16 v[0:15], v[40:43], v[64:67], v[0:15]
	ds_read_b128 v[64:67], v149 offset:25600
	s_waitcnt lgkmcnt(1)
	v_mfma_f32_32x32x16_bf16 v[0:15], v[36:39], v[68:71], v[0:15]
	ds_read_b128 v[68:71], v149 offset:29696
	s_waitcnt lgkmcnt(1)
	v_mfma_f32_32x32x16_bf16 v[0:15], v[24:27], v[64:67], v[0:15]
	v_lshlrev_b64 v[64:65], 12, v[76:77]
	v_and_b32_e32 v66, 0xffff0000, v118
	v_and_b32_e32 v118, 0xffff0000, v119
	v_lshl_add_u64 v[76:77], v[102:103], 0, v[64:65]
	v_lshlrev_b32_e32 v67, 16, v119
	s_waitcnt lgkmcnt(0)
	v_mfma_f32_32x32x16_bf16 v[0:15], v[16:19], v[68:71], v[0:15]
	s_nop 11
	v_fma_f32 v0, v60, v0, v109
	v_fma_f32 v1, v61, v1, v109
	v_fma_f32 v2, v62, v2, v109
	v_fma_f32 v3, v63, v3, v109
	v_mul_f32_e32 v0, v0, v78
	v_mul_f32_e32 v1, v1, v79
	v_fma_f32 v7, v35, v7, v109
	v_mul_f32_e32 v2, v2, v120
	v_mul_f32_e32 v3, v3, v121
	v_cvt_pk_bf16_f32 v230, v0, v1
	v_cvt_pk_bf16_f32 v231, v2, v3
	v_fma_f32 v4, v32, v4, v109
	v_fma_f32 v5, v33, v5, v109
	v_fma_f32 v6, v34, v6, v109
	v_mul_f32_e32 v1, v7, v118
	v_mul_f32_e32 v4, v4, v122
	v_mul_f32_e32 v5, v5, v66
	v_mul_f32_e32 v6, v6, v67
	v_cvt_pk_bf16_f32 v228, v4, v5
	v_cvt_pk_bf16_f32 v229, v6, v1
	s_nop 1
	v_permlane32_swap_b32 v228, v230
	v_permlane32_swap_b32 v229, v231
	v_lshl_add_u64 v[162:163], v[76:77], 0, v[160:161]
	global_store_dwordx4 v[162:163], v[228:231], off
	s_waitcnt vmcnt(15)
; __device__ __forceinline__ unsigned cvt_pk_bf16(float lo, float hi) { unsigned r; asm volatile("v_cvt_pk_bf16_f32 %0, %1, %2" : "=v"(r) : "v"(lo), "v"(hi)); return r; }
; #define LAS __attribute__((address_space(3)))
; __device__ __forceinline__ float bflo(unsigned w) { return __uint_as_float(w << 16); }
; __device__ __forceinline__ float bfhi(unsigned w) { return __uint_as_float(w & 0xffff0000u); }
; __device__ __forceinline__ void spatial_phase(LAS unsigned char* lds, const float* w_s, const float* b_s, const float* normg, const float* ssq, const bf16_t* GVT, bf16_t* U) {
;     ...
;         for (int ib = 0; ib < 4; ++ib) {
;             f32x16 acc = {};
; #pragma unroll
;             for (int kk = 0; kk < 8; ++kk) { const bf16x8 af = *(const LAS bf16x8*)(lds + (2 * kk + hi) * 2048 + (32 * ib + r32) * 16);
;                 acc = __builtin_amdgcn_mfma_f32_32x32x16_bf16(bfr[kk], af, acc, 0, 0, 0); }
;             const int i = 32 * ib + r32; bf16_t* up = U + (size_t)(c * 128 + i) * GMW + g * 256 + 32 * wid + 4 * hi;
; #pragma unroll
;             for (int q4 = 0; q4 < 4; ++q4) { const u32x2 u2 = uu[ib][q4]; const float bb = bsv[ib];
;                 const float o0 = bflo(u2.x) * (acc[4 * q4 + 0] * ng[q4][0] + bb), o1 = bfhi(u2.x) * (acc[4 * q4 + 1] * ng[q4][1] + bb), o2 = bflo(u2.y) * (acc[4 * q4 + 2] * ng[q4][2] + bb), o3 = bfhi(u2.y) * (acc[4 * q4 + 3] * ng[q4][3] + bb);
;                 u32x2 w; w.x = cvt_pk_bf16(o0, o1); w.y = cvt_pk_bf16(o2, o3); *(u32x2*)(up + 8 * q4) = w; }
;         }
;         __syncthreads();
	v_permlane32_swap_b32 v114, v116
	v_permlane32_swap_b32 v115, v117
	v_lshlrev_b32_e32 v0, 16, v116
	v_fma_f32 v1, v28, v8, v109
	v_mul_f32_e32 v0, v1, v0
	v_and_b32_e32 v1, 0xffff0000, v116
	v_fma_f32 v2, v29, v9, v109
	v_mul_f32_e32 v1, v2, v1
	v_lshlrev_b32_e32 v2, 16, v117
	v_fma_f32 v3, v30, v10, v109
	v_mul_f32_e32 v2, v3, v2
	v_and_b32_e32 v3, 0xffff0000, v117
	v_fma_f32 v4, v31, v11, v109
	v_mul_f32_e32 v3, v4, v3
	v_cvt_pk_bf16_f32 v234, v0, v1
	v_cvt_pk_bf16_f32 v235, v2, v3
	v_lshlrev_b32_e32 v0, 16, v114
	v_fma_f32 v1, v20, v12, v109
	v_mul_f32_e32 v0, v1, v0
	v_and_b32_e32 v1, 0xffff0000, v114
	v_fma_f32 v2, v21, v13, v109
	v_mul_f32_e32 v1, v2, v1
	v_lshlrev_b32_e32 v2, 16, v115
	v_fma_f32 v3, v22, v14, v109
	v_mul_f32_e32 v2, v3, v2
	v_and_b32_e32 v3, 0xffff0000, v115
	v_fmac_f32_e32 v109, v23, v15
	v_mul_f32_e32 v3, v109, v3
	v_cvt_pk_bf16_f32 v232, v0, v1
	v_cvt_pk_bf16_f32 v233, v2, v3
	ds_read_b128 v[0:3], v149 offset:1536
	ds_read_b128 v[64:67], v149 offset:5632
	s_waitcnt lgkmcnt(1)
	v_mfma_f32_32x32x16_bf16 v[0:15], v[56:59], v[0:3], 0
	s_waitcnt lgkmcnt(0)
	v_mfma_f32_32x32x16_bf16 v[0:15], v[52:55], v[64:67], v[0:15]
	ds_read_b128 v[52:55], v149 offset:9728
	ds_read_b128 v[56:59], v149 offset:13824
	s_waitcnt lgkmcnt(1)
	v_mfma_f32_32x32x16_bf16 v[0:15], v[48:51], v[52:55], v[0:15]
	s_waitcnt lgkmcnt(0)
	v_mfma_f32_32x32x16_bf16 v[0:15], v[44:47], v[56:59], v[0:15]
	ds_read_b128 v[44:47], v149 offset:17920
	ds_read_b128 v[48:51], v149 offset:22016
	s_nop 1
	v_permlane32_swap_b32 v232, v234
	v_permlane32_swap_b32 v233, v235
	v_lshl_add_u64 v[162:163], v[76:77], 0, v[160:161]
	global_store_dwordx4 v[162:163], v[232:235], off offset:32
	s_waitcnt lgkmcnt(1)
	v_mfma_f32_32x32x16_bf16 v[0:15], v[40:43], v[44:47], v[0:15]
	ds_read_b128 v[40:43], v149 offset:30208
	v_or_b32_e32 v44, 0x60, v108
	s_waitcnt vmcnt(7)
	s_waitcnt vmcnt(7)
	v_permlane32_swap_b32 v110, v112
	v_permlane32_swap_b32 v111, v113
	v_lshlrev_b32_e32 v46, 16, v112
	v_and_b32_e32 v47, 0xffff0000, v112
	v_ashrrev_i32_e32 v45, 31, v44
	s_waitcnt lgkmcnt(1)
	v_mfma_f32_32x32x16_bf16 v[0:15], v[36:39], v[48:51], v[0:15]
	ds_read_b128 v[36:39], v149 offset:26112
	v_lshlrev_b32_e32 v48, 16, v113
	s_waitcnt lgkmcnt(0)
	v_mfma_f32_32x32x16_bf16 v[0:15], v[24:27], v[36:39], v[0:15]
	v_and_b32_e32 v26, 0xffff0000, v113
	v_lshlrev_b64 v[24:25], 12, v[44:45]
	v_lshl_add_u64 v[24:25], v[102:103], 0, v[24:25]
	s_waitcnt vmcnt(7)
	v_and_b32_e32 v36, 0xffff0000, v110
	v_lshlrev_b32_e32 v27, 16, v110
	v_mfma_f32_32x32x16_bf16 v[0:15], v[16:19], v[40:43], v[0:15]
	s_nop 11
	v_fma_f32 v0, v60, v0, v80
	v_fma_f32 v1, v61, v1, v80
	v_fma_f32 v2, v62, v2, v80
	v_fma_f32 v3, v63, v3, v80
	v_mul_f32_e32 v0, v0, v46
	v_mul_f32_e32 v1, v1, v47
	v_mul_f32_e32 v2, v2, v48
	v_mul_f32_e32 v3, v3, v26
	v_cvt_pk_bf16_f32 v238, v0, v1
	v_cvt_pk_bf16_f32 v239, v2, v3
	v_fma_f32 v5, v33, v5, v80
	v_lshlrev_b32_e32 v1, 16, v111
	v_fma_f32 v2, v34, v6, v80
	v_fma_f32 v4, v32, v4, v80
	v_mul_f32_e32 v0, v5, v36
	v_mul_f32_e32 v1, v2, v1
	v_and_b32_e32 v2, 0xffff0000, v111
	v_fma_f32 v3, v35, v7, v80
	v_mul_f32_e32 v4, v4, v27
	v_mul_f32_e32 v2, v3, v2
	v_cvt_pk_bf16_f32 v236, v4, v0
	v_cvt_pk_bf16_f32 v237, v1, v2
	s_nop 1
	v_permlane32_swap_b32 v236, v238
	v_permlane32_swap_b32 v237, v239
	v_lshl_add_u64 v[162:163], v[24:25], 0, v[160:161]
	global_store_dwordx4 v[162:163], v[236:239], off
	s_waitcnt vmcnt(7)
	s_waitcnt vmcnt(7)
	v_permlane32_swap_b32 v104, v106
	v_permlane32_swap_b32 v105, v107
	v_lshlrev_b32_e32 v0, 16, v106
	v_fma_f32 v1, v28, v8, v80
	v_mul_f32_e32 v0, v1, v0
	v_and_b32_e32 v1, 0xffff0000, v106
	v_fma_f32 v2, v29, v9, v80
	v_mul_f32_e32 v1, v2, v1
	v_lshlrev_b32_e32 v2, 16, v107
	v_fma_f32 v3, v30, v10, v80
	v_mul_f32_e32 v2, v3, v2
	v_and_b32_e32 v3, 0xffff0000, v107
	v_fma_f32 v4, v31, v11, v80
	v_mul_f32_e32 v3, v4, v3
	v_cvt_pk_bf16_f32 v242, v0, v1
	v_cvt_pk_bf16_f32 v243, v2, v3
	s_waitcnt vmcnt(7)
	v_lshlrev_b32_e32 v0, 16, v104
	v_fma_f32 v1, v20, v12, v80
	v_mul_f32_e32 v0, v1, v0
	v_and_b32_e32 v1, 0xffff0000, v104
	v_fma_f32 v2, v21, v13, v80
	v_mul_f32_e32 v1, v2, v1
	v_lshlrev_b32_e32 v2, 16, v105
	v_fma_f32 v3, v22, v14, v80
	v_mul_f32_e32 v2, v3, v2
	v_and_b32_e32 v3, 0xffff0000, v105
	v_fmac_f32_e32 v80, v23, v15
	v_mul_f32_e32 v3, v80, v3
	v_cvt_pk_bf16_f32 v240, v0, v1
	v_cvt_pk_bf16_f32 v241, v2, v3
	s_nop 1
	v_permlane32_swap_b32 v240, v242
	v_permlane32_swap_b32 v241, v243
	v_lshl_add_u64 v[162:163], v[24:25], 0, v[160:161]
	global_store_dwordx4 v[162:163], v[240:243], off offset:32
	s_barrier
	s_cbranch_scc0 .LBB0_208
; #define LAS __attribute__((address_space(3)))
; __device__ __forceinline__ void spatial_phase(LAS unsigned char* lds, const float* w_s, const float* b_s, const float* normg, const float* ssq, const bf16_t* GVT, bf16_t* U) {
;     ...
;     for (int unit = blockIdx.x; unit < 528 * 8; unit += gridDim.x) {
;         const int c = unit >> 3, g = unit & 7;
;         const int i_st = tid & 127, cgp = tid >> 7;
;         float sp = 0.f;
;         { const int tk = tid & 127, pg = tid >> 7;
; #pragma unroll
;             for (int p = 0; p < 4; ++p) sp += ssq[(size_t)(pg * 4 + p) * MALL + c * 128 + tk]; }
;         f32x4 wa[4], wb[4];
;         { const float* wrow = w_s + ((size_t)g * 128 + i_st) * 128 + 32 * cgp;
; #pragma unroll
;             for (int q = 0; q < 4; ++q) { wa[q] = *(const f32x4*)(wrow + 8 * q); wb[q] = *(const f32x4*)(wrow + 8 * q + 4); } }
;         bf16x8 bfr[8];
;         { const bf16_t* gp = GVT + ((size_t)c * GMW + g * 256 + 32 * wid + r32) * 128 + 8 * hi;
; #pragma unroll
;             for (int kk = 0; kk < 8; ++kk) bfr[kk] = *(const bf16x8*)(gp + 16 * kk); }
;         u32x2 uu[4][4]; float bsv[4];
; #pragma unroll
;         for (int ib = 0; ib < 4; ++ib) { const int i = 32 * ib + r32; bsv[ib] = b_s[g * 128 + i]; const bf16_t* up = U + (size_t)(c * 128 + i) * GMW + g * 256 + 32 * wid + 4 * hi;
; #pragma unroll
;             for (int q4 = 0; q4 < 4; ++q4) uu[ib][q4] = *(const u32x2*)(up + 8 * q4); }
;         f32x4 ng[4];
; #pragma unroll
;         for (int q4 = 0; q4 < 4; ++q4) ng[q4] = *(const f32x4*)(normg + g * 256 + 32 * wid + 4 * hi + 8 * q4);
;         { LAS float* red = (LAS float*)(lds + 32768); LAS float* rs = red + 512;
;             red[(tid >> 7) * 128 + (tid & 127)] = sp;
;             __syncthreads();
;             if (tid < 128) rs[tid] = rsqrtf(((red[tid] + red[128 + tid]) + (red[256 + tid] + red[384 + tid])) * (1.0f / GMW) + EPS);
;             __syncthreads();
.LBB0_206:
	v_mbcnt_lo_u32_b32 v160, -1, 0
	v_mbcnt_hi_u32_b32 v160, -1, v160
	v_lshrrev_b32_e32 v160, 5, v160
	v_sub_u32_e32 v161, 0, v160
	v_mul_u32_u24_e32 v160, 24, v160
	v_sub_u32_e32 v160, 16, v160
	s_ashr_i32 s6, s13, 3
	s_lshl_b32 s10, s6, 7
	s_ashr_i32 s11, s10, 31
	v_lshl_add_u64 v[0:1], s[10:11], 2, v[82:83]
	s_and_b32 s11, s13, 7
	s_lshl_b32 s8, s11, 8
	v_or_b32_e32 v108, s10, v140
	v_lshl_add_u64 v[16:17], v[86:87], 0, s[8:9]
	s_lshl_b32 s8, s11, 9
	v_ashrrev_i32_e32 v109, 31, v108
	v_lshl_add_u64 v[102:103], v[90:91], 0, s[8:9]
	v_lshlrev_b64 v[20:21], 12, v[108:109]
	s_ashr_i32 s7, s6, 31
	v_lshl_add_u64 v[126:127], v[102:103], 0, v[20:21]
	v_or_b32_e32 v20, s10, v143
	s_lshl_b64 s[6:7], s[6:7], 19
	v_ashrrev_i32_e32 v21, 31, v20
	v_lshl_or_b32 v80, s11, 16, v146
	v_lshlrev_b64 v[16:17], 8, v[16:17]
	v_lshl_add_u64 v[18:19], v[88:89], 0, s[6:7]
	v_lshlrev_b64 v[20:21], 12, v[20:21]
	v_lshl_add_u64 v[2:3], v[0:1], 0, v[94:95]
	v_lshl_add_u64 v[4:5], v[0:1], 0, v[96:97]
	v_lshl_add_u64 v[6:7], v[0:1], 0, v[98:99]
	v_lshl_add_u64 v[0:1], v[0:1], 0, v[100:101]
	v_lshl_add_u64 v[12:13], v[84:85], 0, v[80:81]
	v_lshl_add_u64 v[16:17], v[18:19], 0, v[16:17]
	v_lshl_add_u64 v[20:21], v[102:103], 0, v[20:21]
	global_load_dword v152, v[2:3], off
	global_load_dword v153, v[4:5], off
	global_load_dword v154, v[6:7], off
	global_load_dword v155, v[0:1], off
	global_load_dwordx4 v[64:67], v[12:13], off offset:48
	global_load_dwordx4 v[68:71], v[12:13], off offset:32
	global_load_dwordx4 v[72:75], v[12:13], off offset:16
	global_load_dwordx4 v[76:79], v[12:13], off
	s_nop 0
	global_load_dwordx4 v[0:3], v[12:13], off offset:112
	global_load_dwordx4 v[4:7], v[12:13], off offset:96
	global_load_dwordx4 v[8:11], v[12:13], off offset:80
	s_nop 0
	global_load_dwordx4 v[12:15], v[12:13], off offset:64
	s_nop 0
	global_load_dwordx4 v[56:59], v[16:17], off
	global_load_dwordx4 v[52:55], v[16:17], off offset:32
	global_load_dwordx4 v[48:51], v[16:17], off offset:64
	global_load_dwordx4 v[44:47], v[16:17], off offset:96
	global_load_dwordx4 v[40:43], v[16:17], off offset:128
	global_load_dwordx4 v[36:39], v[16:17], off offset:160
	global_load_dwordx4 v[24:27], v[16:17], off offset:192
	s_nop 0
	global_load_dwordx4 v[16:19], v[16:17], off offset:224
	s_nop 0
	v_lshl_add_u64 v[162:163], v[126:127], 0, v[160:161]
	global_load_dwordx4 v[136:139], v[162:163], off
	global_load_dwordx4 v[132:135], v[162:163], off offset:32
	v_lshl_add_u64 v[162:163], v[20:21], 0, v[160:161]
	global_load_dwordx4 v[128:131], v[162:163], off
	global_load_dwordx4 v[122:125], v[162:163], off offset:32
	v_or_b32_e32 v20, s10, v144
	v_ashrrev_i32_e32 v21, 31, v20
	v_lshlrev_b64 v[20:21], 12, v[20:21]
	v_lshl_add_u64 v[20:21], v[102:103], 0, v[20:21]
	v_lshl_or_b32 v22, v140, 2, s8
	v_lshl_add_u64 v[162:163], v[20:21], 0, v[160:161]
	global_load_dwordx4 v[118:121], v[162:163], off
	global_load_dwordx4 v[114:117], v[162:163], off offset:32
	global_load_dword v151, v22, s[2:3]
	global_load_dword v150, v22, s[2:3] offset:128
	global_load_dword v109, v22, s[2:3] offset:256
	global_load_dword v80, v22, s[2:3] offset:384
	v_or_b32_e32 v20, s10, v145
	v_ashrrev_i32_e32 v21, 31, v20
	v_lshlrev_b64 v[20:21], 12, v[20:21]
	s_lshl_b32 s8, s11, 10
	v_lshl_add_u64 v[104:105], v[102:103], 0, v[20:21]
	v_lshl_add_u64 v[20:21], v[92:93], 0, s[8:9]
	global_load_dwordx4 v[60:63], v[20:21], off
	global_load_dwordx4 v[32:35], v[20:21], off offset:32
	global_load_dwordx4 v[28:31], v[20:21], off offset:64
	s_nop 0
	global_load_dwordx4 v[20:23], v[20:21], off offset:96
	s_nop 0
	v_lshl_add_u64 v[162:163], v[104:105], 0, v[160:161]
	global_load_dwordx4 v[110:113], v[162:163], off
	global_load_dwordx4 v[104:107], v[162:163], off offset:32
	s_nop 0
	s_waitcnt vmcnt(35)
	v_add_f32_e32 v152, 0, v152
	s_waitcnt vmcnt(34)
	v_add_f32_e32 v152, v152, v153
	s_waitcnt vmcnt(33)
	v_add_f32_e32 v152, v152, v154
	s_waitcnt vmcnt(32)
	v_add_f32_e32 v152, v152, v155
	ds_write_b32 v141, v152 offset:32768
	s_waitcnt lgkmcnt(0)
	s_barrier
	s_and_saveexec_b64 s[10:11], vcc
	s_cbranch_execz .LBB0_205
	ds_read2st64_b32 v[152:153], v141 offset0:128 offset1:130
	ds_read2st64_b32 v[154:155], v141 offset0:132 offset1:134
	s_waitcnt lgkmcnt(1)
	v_mov_b32_e32 v156, v152
	s_waitcnt lgkmcnt(0)
	v_mov_b32_e32 v157, v154
	v_mov_b32_e32 v154, v153
	v_pk_add_f32 v[152:153], v[156:157], v[154:155]
	s_nop 0
	v_add_f32_e32 v152, v152, v153
	v_fmamk_f32 v152, v152, 0x3a000000, v147
	v_mul_f32_e32 v153, 0x4b800000, v152
	v_cmp_gt_f32_e64 s[6:7], s12, v152
	s_nop 1
	v_cndmask_b32_e64 v152, v152, v153, s[6:7]
	v_rsq_f32_e32 v152, v152
	s_nop 0
	v_mul_f32_e32 v153, 0x45800000, v152
	v_cndmask_b32_e64 v152, v152, v153, s[6:7]
	ds_write_b32 v141, v152 offset:34816
	s_branch .LBB0_205
